# software-pipelined the two row-rms loops: next rows' 8 loads prefetched into spare VGPRs, counted vmcnt(8) at loop top
# speedup vs baseline: 1.0074x; 1.0074x over previous
.LBB0_128:
	s_cmp_lg_u32 s70, 1
	s_cbranch_scc1 .LBB0_185
	v_mov_b32_e32 v0, v212
	v_readlane_b32 s6, v254, 9
	v_readlane_b32 s7, v254, 10
	v_readfirstlane_b32 s4, v0
	v_readlane_b32 s5, v254, 0
	s_ashr_i32 s4, s4, 6
	s_lshl_b32 s7, s5, 3
	s_add_i32 s7, s7, s4
	s_mov_b64 s[4:5], 0
	s_cmpk_gt_i32 s7, 0x3fff
	s_cbranch_scc1 .LBB0_132
	v_readlane_b32 s12, v254, 13
	s_mul_i32 s8, s68, 0x3000
	v_readlane_b32 s16, v254, 17
	v_and_b32_e32 v18, 63, v0
	s_mul_hi_i32 s9, s68, 0x3000
	v_readlane_b32 s17, v254, 18
	s_add_u32 s8, s16, s8
	s_addc_u32 s9, s17, s9
	v_lshlrev_b32_e32 v0, 4, v18
	v_lshl_add_u64 v[2:3], s[8:9], 0, v[0:1]
	s_mov_b64 s[8:9], 0x2000
	v_add_co_u32_e32 v10, vcc, 0x2000, v2
	v_lshl_add_u64 v[14:15], v[2:3], 0, s[8:9]
	s_nop 0
	v_addc_co_u32_e32 v11, vcc, 0, v3, vcc
	global_load_dwordx4 v[2:5], v[14:15], off offset:1024
	global_load_dwordx4 v[6:9], v[14:15], off offset:2048
	s_nop 0
	global_load_dwordx4 v[10:13], v[10:11], off
	s_nop 0
	global_load_dwordx4 v[14:17], v[14:15], off offset:3072
	s_lshl_b32 s8, s7, 1
	s_ashr_i32 s9, s8, 31
	s_lshl_b32 s6, s6, 4
	s_lshl_b64 s[10:11], s[8:9], 11
	s_add_u32 s4, s4, s10
	s_addc_u32 s5, s5, s11
	v_readlane_b32 s7, v255, 11
	s_add_u32 s4, s7, s4
	v_readlane_b32 s7, v255, 12
	v_lshlrev_b32_e32 v18, 3, v18
	v_mov_b32_e32 v19, v1
	s_addc_u32 s5, s7, s5
	s_ashr_i32 s7, s6, 31
	v_lshl_add_u64 v[50:51], s[4:5], 0, v[18:19]
	s_lshl_b64 s[10:11], s[6:7], 11
	s_lshl_b64 s[4:5], s[8:9], 12
	v_readlane_b32 s9, v255, 13
	s_add_u32 s4, s9, s4
	v_readlane_b32 s9, v255, 14
	v_readlane_b32 s13, v254, 14
	s_addc_u32 s5, s9, s5
	v_lshl_add_u64 v[52:53], s[4:5], 0, v[0:1]
	s_lshl_b64 s[12:13], s[6:7], 12
	v_readlane_b32 s14, v254, 15
	v_readlane_b32 s15, v254, 16
	v_readlane_b32 s18, v254, 19
	v_readlane_b32 s19, v254, 20
	v_readlane_b32 s20, v254, 21
	v_readlane_b32 s21, v254, 22
	v_readlane_b32 s22, v254, 23
	v_readlane_b32 s23, v254, 24
	v_readlane_b32 s24, v254, 25
	v_readlane_b32 s25, v254, 26
	v_readlane_b32 s26, v254, 27
	v_readlane_b32 s27, v254, 28
	global_load_dwordx4 v[116:119], v[52:53], off offset:-4096
	global_load_dwordx4 v[112:115], v[52:53], off offset:-3072
	global_load_dwordx4 v[104:107], v[52:53], off offset:-1024
	global_load_dwordx4 v[108:111], v[52:53], off offset:-2048
	global_load_dwordx4 v[100:103], v[52:53], off
	global_load_dwordx4 v[96:99], v[52:53], off offset:1024
	global_load_dwordx4 v[88:91], v[52:53], off offset:3072
	global_load_dwordx4 v[92:95], v[52:53], off offset:2048
	v_lshl_add_u64 v[52:53], v[52:53], 0, s[12:13]
	s_waitcnt vmcnt(0)
.LBB0_131:
	s_waitcnt vmcnt(8)
	v_mov_b64_e32 v[18:19], v[88:89]
	v_mov_b64_e32 v[20:21], v[90:91]
	v_mov_b64_e32 v[22:23], v[92:93]
	v_mov_b64_e32 v[24:25], v[94:95]
	v_mov_b64_e32 v[26:27], v[96:97]
	v_mov_b64_e32 v[28:29], v[98:99]
	v_mov_b64_e32 v[30:31], v[100:101]
	v_mov_b64_e32 v[32:33], v[102:103]
	v_mov_b64_e32 v[34:35], v[104:105]
	v_mov_b64_e32 v[36:37], v[106:107]
	v_mov_b64_e32 v[38:39], v[108:109]
	v_mov_b64_e32 v[40:41], v[110:111]
	v_mov_b64_e32 v[42:43], v[112:113]
	v_mov_b64_e32 v[44:45], v[114:115]
	v_mov_b64_e32 v[46:47], v[116:117]
	v_mov_b64_e32 v[48:49], v[118:119]
	s_add_i32 s8, s8, s6
	s_cmp_lt_i32 s8, 0x8000
	s_cbranch_scc0 .Lrms_nopf_a
	global_load_dwordx4 v[116:119], v[52:53], off offset:-4096
	global_load_dwordx4 v[112:115], v[52:53], off offset:-3072
	global_load_dwordx4 v[104:107], v[52:53], off offset:-1024
	global_load_dwordx4 v[108:111], v[52:53], off offset:-2048
	global_load_dwordx4 v[100:103], v[52:53], off
	global_load_dwordx4 v[96:99], v[52:53], off offset:1024
	global_load_dwordx4 v[88:91], v[52:53], off offset:3072
	global_load_dwordx4 v[92:95], v[52:53], off offset:2048
	v_lshl_add_u64 v[52:53], v[52:53], 0, s[12:13]
.Lrms_nopf_a:
	v_pk_mul_f32 v[54:55], v[48:49], v[48:49]
	v_pk_mul_f32 v[56:57], v[46:47], v[46:47]
	v_pk_mul_f32 v[58:59], v[44:45], v[44:45]
	v_pk_mul_f32 v[60:61], v[42:43], v[42:43]
	v_mul_f32_e32 v0, v39, v39
	v_mul_f32_e32 v62, v41, v41
	v_pk_mul_f32 v[64:65], v[32:33], v[32:33]
	v_pk_mul_f32 v[66:67], v[30:31], v[30:31]
	v_pk_mul_f32 v[68:69], v[28:29], v[28:29]
	v_pk_mul_f32 v[70:71], v[26:27], v[26:27]
	v_mul_f32_e32 v81, v36, v36
	v_mul_f32_e32 v82, v37, v37
	v_pk_mov_b32 v[76:77], v[56:57], v[54:55] op_sel:[1,0]
	v_mov_b32_e32 v57, v55
	v_pk_mov_b32 v[54:55], v[60:61], v[58:59] op_sel:[1,0]
	v_mov_b32_e32 v61, v59
	v_pk_fma_f32 v[58:59], v[38:39], v[38:39], v[0:1] op_sel_hi:[1,1,0]
	v_pk_fma_f32 v[62:63], v[40:41], v[40:41], v[62:63] op_sel_hi:[1,1,0]
	v_pk_mov_b32 v[78:79], v[66:67], v[64:65] op_sel:[1,0]
	v_mov_b32_e32 v67, v65
	v_pk_mov_b32 v[64:65], v[70:71], v[68:69] op_sel:[1,0]
	v_mov_b32_e32 v71, v69
	v_mul_f32_e32 v75, v34, v34
	v_mul_f32_e32 v72, v23, v23
	v_mul_f32_e32 v74, v25, v25
	v_pk_add_f32 v[56:57], v[76:77], v[56:57]
	v_pk_add_f32 v[54:55], v[54:55], v[60:61]
	v_mov_b32_e32 v59, v81
	v_mov_b32_e32 v63, v82
	v_pk_add_f32 v[60:61], v[78:79], v[66:67]
	v_pk_add_f32 v[64:65], v[64:65], v[70:71]
	v_mul_f32_e32 v80, v35, v35
	v_mul_f32_e32 v83, v18, v18
	v_mul_f32_e32 v84, v19, v19
	v_mul_f32_e32 v85, v20, v20
	v_mul_f32_e32 v86, v21, v21
	v_pk_fma_f32 v[68:69], v[22:23], v[22:23], v[72:73] op_sel_hi:[1,1,0]
	v_pk_fma_f32 v[72:73], v[24:25], v[24:25], v[74:75] op_sel_hi:[1,1,0]
	v_pk_add_f32 v[56:57], v[56:57], v[56:57] op_sel:[0,1] op_sel_hi:[1,0]
	v_pk_add_f32 v[54:55], v[54:55], v[54:55] op_sel:[0,1] op_sel_hi:[1,0]
	v_pk_add_f32 v[58:59], v[58:59], v[62:63]
	v_pk_add_f32 v[60:61], v[60:61], v[60:61] op_sel:[0,1] op_sel_hi:[1,0]
	v_pk_add_f32 v[62:63], v[64:65], v[64:65] op_sel:[0,1] op_sel_hi:[1,0]
	v_mov_b32_e32 v69, v85
	v_mov_b32_e32 v73, v86
	v_mov_b32_e32 v57, v75
	v_mov_b32_e32 v55, v80
	v_mov_b32_e32 v61, v83
	v_mov_b32_e32 v63, v84
	v_pk_add_f32 v[64:65], v[68:69], v[72:73]
	v_pk_add_f32 v[54:55], v[56:57], v[54:55]
	v_pk_add_f32 v[56:57], v[60:61], v[62:63]
	v_pk_add_f32 v[54:55], v[54:55], v[58:59]
	v_pk_add_f32 v[56:57], v[56:57], v[64:65]
	v_add_f32_e32 v0, v54, v55
	v_add_f32_e32 v54, v56, v57
	s_nop 0
	v_add_f32_dpp v0, v0, v0 row_ror:8 row_mask:0xf bank_mask:0xf bound_ctrl:1
	v_add_f32_dpp v54, v54, v54 row_ror:8 row_mask:0xf bank_mask:0xf bound_ctrl:1
	s_nop 0
	v_add_f32_dpp v0, v0, v0 row_ror:4 row_mask:0xf bank_mask:0xf bound_ctrl:1
	v_add_f32_dpp v54, v54, v54 row_ror:4 row_mask:0xf bank_mask:0xf bound_ctrl:1
	s_nop 0
	v_add_f32_dpp v0, v0, v0 row_ror:2 row_mask:0xf bank_mask:0xf bound_ctrl:1
	v_add_f32_dpp v54, v54, v54 row_ror:2 row_mask:0xf bank_mask:0xf bound_ctrl:1
	s_nop 0
	v_add_f32_dpp v0, v0, v0 row_ror:1 row_mask:0xf bank_mask:0xf bound_ctrl:1
	v_add_f32_dpp v54, v54, v54 row_ror:1 row_mask:0xf bank_mask:0xf bound_ctrl:1
	v_readlane_b32 s7, v0, 16
	v_readlane_b32 s9, v0, 48
	v_readlane_b32 s16, v54, 16
	v_readlane_b32 s17, v54, 48
	v_readlane_b32 s4, v0, 0
	v_readlane_b32 s5, v0, 32
	v_readlane_b32 s14, v54, 0
	v_readlane_b32 s15, v54, 32
	v_mov_b32_e32 v54, s7
	v_mov_b32_e32 v55, s9
	v_mov_b32_e32 v56, s16
	v_mov_b32_e32 v57, s17
	v_pk_add_f32 v[54:55], s[4:5], v[54:55]
	v_pk_add_f32 v[56:57], s[14:15], v[56:57]
	v_add_f32_e32 v0, v54, v55
	v_add_f32_e32 v54, v56, v57
	v_fmamk_f32 v0, v0, 0x3a800000, v213
	v_fmamk_f32 v54, v54, 0x3a800000, v213
	v_mul_f32_e32 v55, 0x4b800000, v0
	v_mul_f32_e32 v56, 0x4b800000, v54
	v_cmp_gt_f32_e32 vcc, s89, v54
	v_cmp_gt_f32_e64 s[4:5], s89, v0
	s_nop 0
	v_cndmask_b32_e32 v54, v54, v56, vcc
	v_cndmask_b32_e64 v0, v0, v55, s[4:5]
	v_rsq_f32_e32 v0, v0
	v_rsq_f32_e32 v54, v54
	v_mul_f32_e32 v55, 0x45800000, v0
	v_mul_f32_e32 v56, 0x45800000, v54
	v_cndmask_b32_e64 v0, v0, v55, s[4:5]
	v_cndmask_b32_e32 v54, v54, v56, vcc
	v_mul_f32_e32 v46, v46, v0
	v_mul_f32_e32 v47, v47, v0
	v_mul_f32_e32 v48, v48, v0
	v_mul_f32_e32 v49, v49, v0
	v_mul_f32_e32 v18, v18, v54
	v_mul_f32_e32 v19, v19, v54
	v_mul_f32_e32 v42, v42, v0
	v_mul_f32_e32 v43, v43, v0
	v_mul_f32_e32 v44, v44, v0
	v_mul_f32_e32 v45, v45, v0
	v_mul_f32_e32 v38, v38, v0
	v_mul_f32_e32 v39, v39, v0
	v_mul_f32_e32 v40, v40, v0
	v_mul_f32_e32 v41, v41, v0
	v_mul_f32_e32 v34, v34, v0
	v_mul_f32_e32 v35, v35, v0
	v_mul_f32_e32 v36, v36, v0
	v_mul_f32_e32 v0, v37, v0
	v_mul_f32_e32 v30, v30, v54
	v_mul_f32_e32 v31, v31, v54
	v_mul_f32_e32 v32, v32, v54
	v_mul_f32_e32 v33, v33, v54
	v_mul_f32_e32 v26, v26, v54
	v_mul_f32_e32 v27, v27, v54
	v_mul_f32_e32 v28, v28, v54
	v_mul_f32_e32 v29, v29, v54
	v_mul_f32_e32 v22, v22, v54
	v_mul_f32_e32 v23, v23, v54
	v_mul_f32_e32 v24, v24, v54
	v_mul_f32_e32 v25, v25, v54
	v_mul_f32_e32 v20, v20, v54
	v_mul_f32_e32 v21, v21, v54
	v_mul_f32_e32 v37, v10, v46
	v_mul_f32_e32 v46, v11, v47
	v_mul_f32_e32 v47, v12, v48
	v_mul_f32_e32 v48, v13, v49
	v_mul_f32_e32 v49, v14, v18
	v_mul_f32_e32 v54, v15, v19
	v_cvt_pk_bf16_f32 v18, v37, v46
	v_cvt_pk_bf16_f32 v19, v47, v48
	v_mul_f32_e32 v42, v2, v42
	v_mul_f32_e32 v43, v3, v43
	v_mul_f32_e32 v44, v4, v44
	v_mul_f32_e32 v45, v5, v45
	global_store_dwordx2 v[50:51], v[18:19], off offset:-2048
	v_cvt_pk_bf16_f32 v18, v42, v43
	v_cvt_pk_bf16_f32 v19, v44, v45
	v_mul_f32_e32 v38, v6, v38
	v_mul_f32_e32 v39, v7, v39
	v_mul_f32_e32 v40, v8, v40
	v_mul_f32_e32 v41, v9, v41
	global_store_dwordx2 v[50:51], v[18:19], off offset:-1536
	v_cvt_pk_bf16_f32 v18, v38, v39
	v_cvt_pk_bf16_f32 v19, v40, v41
	v_mul_f32_e32 v34, v14, v34
	v_mul_f32_e32 v35, v15, v35
	v_mul_f32_e32 v36, v16, v36
	v_mul_f32_e32 v0, v17, v0
	global_store_dwordx2 v[50:51], v[18:19], off offset:-1024
	v_cvt_pk_bf16_f32 v18, v34, v35
	v_cvt_pk_bf16_f32 v19, v36, v0
	v_mul_f32_e32 v30, v10, v30
	v_mul_f32_e32 v31, v11, v31
	v_mul_f32_e32 v32, v12, v32
	v_mul_f32_e32 v33, v13, v33
	global_store_dwordx2 v[50:51], v[18:19], off offset:-512
	v_cvt_pk_bf16_f32 v18, v30, v31
	v_cvt_pk_bf16_f32 v19, v32, v33
	v_mul_f32_e32 v26, v2, v26
	v_mul_f32_e32 v27, v3, v27
	v_mul_f32_e32 v28, v4, v28
	v_mul_f32_e32 v29, v5, v29
	global_store_dwordx2 v[50:51], v[18:19], off
	v_cvt_pk_bf16_f32 v18, v26, v27
	v_cvt_pk_bf16_f32 v19, v28, v29
	v_mul_f32_e32 v22, v6, v22
	v_mul_f32_e32 v23, v7, v23
	v_mul_f32_e32 v24, v8, v24
	v_mul_f32_e32 v25, v9, v25
	global_store_dwordx2 v[50:51], v[18:19], off offset:512
	v_cvt_pk_bf16_f32 v18, v22, v23
	v_cvt_pk_bf16_f32 v19, v24, v25
	v_mul_f32_e32 v20, v16, v20
	v_mul_f32_e32 v21, v17, v21
	global_store_dwordx2 v[50:51], v[18:19], off offset:1024
	v_cvt_pk_bf16_f32 v18, v49, v54
	v_cvt_pk_bf16_f32 v19, v20, v21
	global_store_dwordx2 v[50:51], v[18:19], off offset:1536
	v_lshl_add_u64 v[50:51], v[50:51], 0, s[10:11]
	s_cbranch_scc1 .LBB0_131

.LBB0_336:
	v_mov_b32_e32 v0, v212
	v_readlane_b32 s6, v254, 9
	v_readfirstlane_b32 s4, v0
	s_ashr_i32 s5, s4, 6
	s_mov_b32 s4, s6
	v_readlane_b32 s6, v254, 0
	s_lshl_b32 s6, s6, 3
	s_add_i32 s5, s6, s5
	s_mov_b64 s[8:9], 0
	s_cmpk_gt_i32 s5, 0x3fff
	v_readlane_b32 s7, v254, 10
	s_cbranch_scc1 .LBB0_339
	v_readlane_b32 s12, v254, 13
	s_mul_i32 s6, s68, 0x3000
	v_readlane_b32 s16, v254, 17
	v_and_b32_e32 v18, 63, v0
	s_mul_hi_i32 s7, s68, 0x3000
	v_readlane_b32 s17, v254, 18
	s_add_u32 s6, s16, s6
	s_addc_u32 s7, s17, s7
	v_lshlrev_b32_e32 v0, 4, v18
	v_lshl_add_u64 v[2:3], s[6:7], 0, v[0:1]
	s_mov_b64 s[6:7], 0x1000
	v_add_co_u32_e32 v10, vcc, 0x1000, v2
	v_lshl_add_u64 v[14:15], v[2:3], 0, s[6:7]
	s_nop 0
	v_addc_co_u32_e32 v11, vcc, 0, v3, vcc
	global_load_dwordx4 v[2:5], v[14:15], off offset:1024
	global_load_dwordx4 v[6:9], v[14:15], off offset:2048
	s_nop 0
	global_load_dwordx4 v[10:13], v[10:11], off
	s_nop 0
	global_load_dwordx4 v[14:17], v[14:15], off offset:3072
	s_lshl_b32 s6, s5, 1
	s_ashr_i32 s7, s6, 31
	s_lshl_b32 s4, s4, 4
	s_lshl_b64 s[10:11], s[6:7], 11
	s_add_u32 s5, s8, s10
	s_addc_u32 s9, s9, s11
	v_readlane_b32 s8, v255, 11
	s_add_u32 s8, s8, s5
	v_readlane_b32 s5, v255, 12
	v_lshlrev_b32_e32 v18, 3, v18
	v_mov_b32_e32 v19, v1
	s_addc_u32 s9, s5, s9
	s_ashr_i32 s5, s4, 31
	v_lshl_add_u64 v[18:19], s[8:9], 0, v[18:19]
	s_lshl_b64 s[8:9], s[4:5], 11
	s_lshl_b64 s[10:11], s[6:7], 12
	v_readlane_b32 s7, v255, 13
	s_add_u32 s10, s7, s10
	v_readlane_b32 s7, v255, 14
	s_addc_u32 s11, s7, s11
	v_lshl_add_u64 v[20:21], s[10:11], 0, v[0:1]
	s_lshl_b64 s[10:11], s[4:5], 12
	v_readlane_b32 s13, v254, 14
	v_readlane_b32 s14, v254, 15
	v_readlane_b32 s15, v254, 16
	v_readlane_b32 s18, v254, 19
	v_readlane_b32 s19, v254, 20
	v_readlane_b32 s20, v254, 21
	v_readlane_b32 s21, v254, 22
	v_readlane_b32 s22, v254, 23
	v_readlane_b32 s23, v254, 24
	v_readlane_b32 s24, v254, 25
	v_readlane_b32 s25, v254, 26
	v_readlane_b32 s26, v254, 27
	v_readlane_b32 s27, v254, 28
	global_load_dwordx4 v[88:91], v[20:21], off offset:-4096
	global_load_dwordx4 v[92:95], v[20:21], off offset:-3072
	global_load_dwordx4 v[96:99], v[20:21], off offset:-2048
	global_load_dwordx4 v[100:103], v[20:21], off offset:-1024
	global_load_dwordx4 v[104:107], v[20:21], off
	global_load_dwordx4 v[108:111], v[20:21], off offset:1024
	global_load_dwordx4 v[112:115], v[20:21], off offset:2048
	global_load_dwordx4 v[116:119], v[20:21], off offset:3072
	v_lshl_add_u64 v[20:21], v[20:21], 0, s[10:11]
	s_waitcnt vmcnt(0)
.LBB0_338:
	s_waitcnt vmcnt(8)
	v_mov_b64_e32 v[22:23], v[88:89]
	v_mov_b64_e32 v[24:25], v[90:91]
	v_mov_b64_e32 v[26:27], v[92:93]
	v_mov_b64_e32 v[28:29], v[94:95]
	v_mov_b64_e32 v[30:31], v[96:97]
	v_mov_b64_e32 v[32:33], v[98:99]
	v_mov_b64_e32 v[34:35], v[100:101]
	v_mov_b64_e32 v[36:37], v[102:103]
	v_mov_b64_e32 v[38:39], v[104:105]
	v_mov_b64_e32 v[40:41], v[106:107]
	v_mov_b64_e32 v[42:43], v[108:109]
	v_mov_b64_e32 v[44:45], v[110:111]
	v_mov_b64_e32 v[46:47], v[112:113]
	v_mov_b64_e32 v[48:49], v[114:115]
	v_mov_b64_e32 v[50:51], v[116:117]
	v_mov_b64_e32 v[52:53], v[118:119]
	s_add_i32 s6, s6, s4
	s_cmp_lt_i32 s6, 0x8000
	s_cbranch_scc0 .Lrms_nopf_b
	global_load_dwordx4 v[88:91], v[20:21], off offset:-4096
	global_load_dwordx4 v[92:95], v[20:21], off offset:-3072
	global_load_dwordx4 v[96:99], v[20:21], off offset:-2048
	global_load_dwordx4 v[100:103], v[20:21], off offset:-1024
	global_load_dwordx4 v[104:107], v[20:21], off
	global_load_dwordx4 v[108:111], v[20:21], off offset:1024
	global_load_dwordx4 v[112:115], v[20:21], off offset:2048
	global_load_dwordx4 v[116:119], v[20:21], off offset:3072
	v_lshl_add_u64 v[20:21], v[20:21], 0, s[10:11]
.Lrms_nopf_b:
	v_pk_mul_f32 v[54:55], v[24:25], v[24:25]
	v_pk_mul_f32 v[56:57], v[22:23], v[22:23]
	v_mul_f32_e32 v0, v34, v34
	v_pk_mov_b32 v[58:59], v[56:57], v[54:55] op_sel:[1,0]
	v_mov_b32_e32 v57, v55
	v_pk_add_f32 v[54:55], v[58:59], v[56:57]
	v_pk_mul_f32 v[56:57], v[28:29], v[28:29]
	v_pk_mul_f32 v[58:59], v[26:27], v[26:27]
	v_pk_add_f32 v[54:55], v[54:55], v[54:55] op_sel:[0,1] op_sel_hi:[1,0]
	v_pk_mov_b32 v[60:61], v[58:59], v[56:57] op_sel:[1,0]
	v_mov_b32_e32 v59, v57
	v_pk_add_f32 v[56:57], v[60:61], v[58:59]
	v_mul_f32_e32 v58, v35, v35
	v_pk_add_f32 v[56:57], v[56:57], v[56:57] op_sel:[0,1] op_sel_hi:[1,0]
	v_mov_b32_e32 v55, v0
	v_mov_b32_e32 v57, v58
	v_mul_f32_e32 v0, v31, v31
	v_mul_f32_e32 v59, v36, v36
	v_pk_add_f32 v[54:55], v[54:55], v[56:57]
	v_pk_fma_f32 v[56:57], v[30:31], v[30:31], v[0:1] op_sel_hi:[1,1,0]
	v_mul_f32_e32 v0, v33, v33
	v_mul_f32_e32 v60, v37, v37
	v_mov_b32_e32 v57, v59
	v_pk_fma_f32 v[58:59], v[32:33], v[32:33], v[0:1] op_sel_hi:[1,1,0]
	v_mul_f32_e32 v0, v50, v50
	v_mov_b32_e32 v59, v60
	v_pk_add_f32 v[56:57], v[56:57], v[58:59]
	s_nop 0
	v_pk_add_f32 v[54:55], v[54:55], v[56:57]
	v_pk_mul_f32 v[56:57], v[38:39], v[38:39]
	v_add_f32_e32 v62, v54, v55
	v_pk_mul_f32 v[54:55], v[40:41], v[40:41]
	s_nop 0
	v_pk_mov_b32 v[58:59], v[56:57], v[54:55] op_sel:[1,0]
	v_mov_b32_e32 v57, v55
	v_pk_add_f32 v[54:55], v[58:59], v[56:57]
	v_pk_mul_f32 v[56:57], v[44:45], v[44:45]
	v_pk_mul_f32 v[58:59], v[42:43], v[42:43]
	v_pk_add_f32 v[54:55], v[54:55], v[54:55] op_sel:[0,1] op_sel_hi:[1,0]
	v_pk_mov_b32 v[60:61], v[58:59], v[56:57] op_sel:[1,0]
	v_mov_b32_e32 v59, v57
	v_pk_add_f32 v[56:57], v[60:61], v[58:59]
	v_mul_f32_e32 v58, v51, v51
	v_pk_add_f32 v[56:57], v[56:57], v[56:57] op_sel:[0,1] op_sel_hi:[1,0]
	v_mov_b32_e32 v55, v0
	v_mov_b32_e32 v57, v58
	v_mul_f32_e32 v0, v47, v47
	v_mul_f32_e32 v59, v52, v52
	v_pk_add_f32 v[54:55], v[54:55], v[56:57]
	v_pk_fma_f32 v[56:57], v[46:47], v[46:47], v[0:1] op_sel_hi:[1,1,0]
	v_mul_f32_e32 v0, v49, v49
	v_mul_f32_e32 v60, v53, v53
	v_mov_b32_e32 v57, v59
	v_pk_fma_f32 v[58:59], v[48:49], v[48:49], v[0:1] op_sel_hi:[1,1,0]
	s_nop 0
	v_mov_b32_e32 v59, v60
	v_pk_add_f32 v[56:57], v[56:57], v[58:59]
	s_nop 0
	v_pk_add_f32 v[54:55], v[54:55], v[56:57]
	s_nop 0
	v_add_f32_e32 v0, v54, v55
	v_add_f32_dpp v54, v62, v62 row_ror:8 row_mask:0xf bank_mask:0xf bound_ctrl:1
	s_nop 0
	v_add_f32_dpp v0, v0, v0 row_ror:8 row_mask:0xf bank_mask:0xf bound_ctrl:1
	v_add_f32_dpp v54, v54, v54 row_ror:4 row_mask:0xf bank_mask:0xf bound_ctrl:1
	s_nop 0
	v_add_f32_dpp v0, v0, v0 row_ror:4 row_mask:0xf bank_mask:0xf bound_ctrl:1
	v_add_f32_dpp v54, v54, v54 row_ror:2 row_mask:0xf bank_mask:0xf bound_ctrl:1
	s_nop 0
	v_add_f32_dpp v0, v0, v0 row_ror:2 row_mask:0xf bank_mask:0xf bound_ctrl:1
	v_add_f32_dpp v54, v54, v54 row_ror:1 row_mask:0xf bank_mask:0xf bound_ctrl:1
	s_nop 0
	v_readlane_b32 s5, v54, 16
	v_readlane_b32 s7, v54, 48
	v_readlane_b32 s12, v54, 0
	v_readlane_b32 s13, v54, 32
	v_mov_b32_e32 v54, s5
	v_mov_b32_e32 v55, s7
	v_pk_add_f32 v[54:55], s[12:13], v[54:55]
	v_add_f32_dpp v0, v0, v0 row_ror:1 row_mask:0xf bank_mask:0xf bound_ctrl:1
	v_add_f32_e32 v54, v54, v55
	v_fmamk_f32 v54, v54, 0x3a800000, v213
	v_cmp_gt_f32_e32 vcc, s89, v54
	v_mul_f32_e32 v55, 0x4b800000, v54
	v_readlane_b32 s5, v0, 16
	v_cndmask_b32_e32 v54, v54, v55, vcc
	v_rsq_f32_e32 v54, v54
	v_readlane_b32 s7, v0, 48
	v_readlane_b32 s12, v0, 0
	v_readlane_b32 s13, v0, 32
	v_mul_f32_e32 v55, 0x45800000, v54
	v_cndmask_b32_e32 v54, v54, v55, vcc
	v_mul_f32_e32 v22, v22, v54
	v_mul_f32_e32 v23, v23, v54
	v_mul_f32_e32 v22, v10, v22
	v_mul_f32_e32 v23, v11, v23
	v_cvt_pk_bf16_f32 v22, v22, v23
	v_mul_f32_e32 v23, v24, v54
	v_mul_f32_e32 v23, v12, v23
	v_mul_f32_e32 v24, v25, v54
	v_mul_f32_e32 v24, v13, v24
	v_cvt_pk_bf16_f32 v23, v23, v24
	global_store_dwordx2 v[18:19], v[22:23], off offset:-2048
	v_mul_f32_e32 v22, v26, v54
	v_mul_f32_e32 v23, v27, v54
	v_mul_f32_e32 v22, v2, v22
	v_mul_f32_e32 v23, v3, v23
	v_cvt_pk_bf16_f32 v22, v22, v23
	v_mul_f32_e32 v23, v28, v54
	v_mul_f32_e32 v23, v4, v23
	v_mul_f32_e32 v24, v29, v54
	v_mul_f32_e32 v24, v5, v24
	v_cvt_pk_bf16_f32 v23, v23, v24
	global_store_dwordx2 v[18:19], v[22:23], off offset:-1536
	v_mul_f32_e32 v22, v30, v54
	v_mul_f32_e32 v23, v31, v54
	v_mul_f32_e32 v22, v6, v22
	v_mul_f32_e32 v23, v7, v23
	v_cvt_pk_bf16_f32 v22, v22, v23
	v_mul_f32_e32 v23, v32, v54
	v_mul_f32_e32 v23, v8, v23
	v_mul_f32_e32 v24, v33, v54
	v_mul_f32_e32 v24, v9, v24
	v_cvt_pk_bf16_f32 v23, v23, v24
	global_store_dwordx2 v[18:19], v[22:23], off offset:-1024
	v_mul_f32_e32 v22, v34, v54
	v_mul_f32_e32 v23, v35, v54
	v_mul_f32_e32 v22, v14, v22
	v_mul_f32_e32 v23, v15, v23
	v_cvt_pk_bf16_f32 v22, v22, v23
	v_mul_f32_e32 v23, v36, v54
	v_mul_f32_e32 v23, v16, v23
	v_mul_f32_e32 v24, v37, v54
	v_mul_f32_e32 v24, v17, v24
	v_cvt_pk_bf16_f32 v23, v23, v24
	global_store_dwordx2 v[18:19], v[22:23], off offset:-512
	v_mov_b32_e32 v22, s5
	v_mov_b32_e32 v23, s7
	v_pk_add_f32 v[22:23], s[12:13], v[22:23]
	s_nop 0
	v_add_f32_e32 v0, v22, v23
	v_fmamk_f32 v0, v0, 0x3a800000, v213
	v_cmp_gt_f32_e32 vcc, s89, v0
	v_mul_f32_e32 v22, 0x4b800000, v0
	s_nop 0
	v_cndmask_b32_e32 v0, v0, v22, vcc
	v_rsq_f32_e32 v0, v0
	s_nop 0
	v_mul_f32_e32 v22, 0x45800000, v0
	v_cndmask_b32_e32 v0, v0, v22, vcc
	v_mul_f32_e32 v22, v38, v0
	v_mul_f32_e32 v23, v39, v0
	v_mul_f32_e32 v22, v10, v22
	v_mul_f32_e32 v23, v11, v23
	v_cvt_pk_bf16_f32 v22, v22, v23
	v_mul_f32_e32 v23, v40, v0
	v_mul_f32_e32 v23, v12, v23
	v_mul_f32_e32 v24, v41, v0
	v_mul_f32_e32 v24, v13, v24
	v_cvt_pk_bf16_f32 v23, v23, v24
	global_store_dwordx2 v[18:19], v[22:23], off
	v_mul_f32_e32 v22, v42, v0
	v_mul_f32_e32 v23, v43, v0
	v_mul_f32_e32 v22, v2, v22
	v_mul_f32_e32 v23, v3, v23
	v_cvt_pk_bf16_f32 v22, v22, v23
	v_mul_f32_e32 v23, v44, v0
	v_mul_f32_e32 v23, v4, v23
	v_mul_f32_e32 v24, v45, v0
	v_mul_f32_e32 v24, v5, v24
	v_cvt_pk_bf16_f32 v23, v23, v24
	global_store_dwordx2 v[18:19], v[22:23], off offset:512
	v_mul_f32_e32 v22, v46, v0
	v_mul_f32_e32 v23, v47, v0
	v_mul_f32_e32 v22, v6, v22
	v_mul_f32_e32 v23, v7, v23
	v_cvt_pk_bf16_f32 v22, v22, v23
	v_mul_f32_e32 v23, v48, v0
	v_mul_f32_e32 v23, v8, v23
	v_mul_f32_e32 v24, v49, v0
	v_mul_f32_e32 v24, v9, v24
	v_cvt_pk_bf16_f32 v23, v23, v24
	global_store_dwordx2 v[18:19], v[22:23], off offset:1024
	v_mul_f32_e32 v22, v50, v0
	v_mul_f32_e32 v23, v51, v0
	v_mul_f32_e32 v22, v14, v22
	v_mul_f32_e32 v23, v15, v23
	v_cvt_pk_bf16_f32 v22, v22, v23
	v_mul_f32_e32 v23, v52, v0
	v_mul_f32_e32 v23, v16, v23
	v_mul_f32_e32 v0, v53, v0
	v_mul_f32_e32 v0, v17, v0
	v_cvt_pk_bf16_f32 v23, v23, v0
	global_store_dwordx2 v[18:19], v[22:23], off offset:1536
	v_lshl_add_u64 v[18:19], v[18:19], 0, s[8:9]
	s_cbranch_scc1 .LBB0_338
